# DSA attention softmax pass de-serialised: 32 LDS score reads issued up front, exp in groups of four with independent masks, one pass instead of 16 read round trips
# speedup vs baseline: 1.0127x; 1.0127x over previous
; __device__ __forceinline__ void dsa_item(const KP& p, int b, int tile, char* smem) {
;     ...
;     float sum = 0.f;
; #pragma unroll 4
;     for (int k = 0; k < 32; ++k) {
;       const int i = lane + 64 * k;
;       const float v = pbuf[i];
;       const float e = (v > -1e29f) ? __expf(v - mxh) : 0.f;
;       pbuf[i] = e;
;       sum += e;
;     }
.LBB0_1510:
	ds_read2st64_b32 v[16:17], v168 offset1:1
	ds_read2st64_b32 v[18:19], v168 offset0:2 offset1:3
	ds_read2st64_b32 v[20:21], v168 offset0:4 offset1:5
	ds_read2st64_b32 v[22:23], v168 offset0:6 offset1:7
	ds_read2st64_b32 v[24:25], v168 offset0:8 offset1:9
	ds_read2st64_b32 v[26:27], v168 offset0:10 offset1:11
	ds_read2st64_b32 v[28:29], v168 offset0:12 offset1:13
	ds_read2st64_b32 v[30:31], v168 offset0:14 offset1:15
	ds_read2st64_b32 v[32:33], v168 offset0:16 offset1:17
	ds_read2st64_b32 v[34:35], v168 offset0:18 offset1:19
	ds_read2st64_b32 v[36:37], v168 offset0:20 offset1:21
	ds_read2st64_b32 v[38:39], v168 offset0:22 offset1:23
	ds_read2st64_b32 v[40:41], v168 offset0:24 offset1:25
	ds_read2st64_b32 v[42:43], v168 offset0:26 offset1:27
	ds_read2st64_b32 v[44:45], v168 offset0:28 offset1:29
	ds_read2st64_b32 v[46:47], v168 offset0:30 offset1:31
	s_waitcnt lgkmcnt(14)
	v_cmp_lt_f32_e32 vcc, s75, v16
	v_cmp_lt_f32_e64 s[2:3], s75, v17
	v_cmp_lt_f32_e64 s[14:15], s75, v18
	v_cmp_lt_f32_e64 s[46:47], s75, v19
	v_sub_f32_e32 v16, v16, v2
	v_sub_f32_e32 v17, v17, v2
	v_sub_f32_e32 v18, v18, v2
	v_sub_f32_e32 v19, v19, v2
	v_mul_f32_e32 v16, 0x3fb8aa3b, v16
	v_mul_f32_e32 v17, 0x3fb8aa3b, v17
	v_mul_f32_e32 v18, 0x3fb8aa3b, v18
	v_mul_f32_e32 v19, 0x3fb8aa3b, v19
	v_exp_f32_e32 v16, v16
	v_exp_f32_e32 v17, v17
	v_exp_f32_e32 v18, v18
	v_exp_f32_e32 v19, v19
	v_cndmask_b32_e32 v16, 0, v16, vcc
	v_cndmask_b32_e64 v17, 0, v17, s[2:3]
	v_cndmask_b32_e64 v18, 0, v18, s[14:15]
	v_cndmask_b32_e64 v19, 0, v19, s[46:47]
	v_add_f32_e32 v3, v3, v16
	v_add_f32_e32 v3, v3, v17
	v_add_f32_e32 v3, v3, v18
	v_add_f32_e32 v3, v3, v19
	s_waitcnt lgkmcnt(12)
	v_cmp_lt_f32_e32 vcc, s75, v20
	v_cmp_lt_f32_e64 s[2:3], s75, v21
	v_cmp_lt_f32_e64 s[14:15], s75, v22
	v_cmp_lt_f32_e64 s[46:47], s75, v23
	v_sub_f32_e32 v20, v20, v2
	v_sub_f32_e32 v21, v21, v2
	v_sub_f32_e32 v22, v22, v2
	v_sub_f32_e32 v23, v23, v2
	v_mul_f32_e32 v20, 0x3fb8aa3b, v20
	v_mul_f32_e32 v21, 0x3fb8aa3b, v21
	v_mul_f32_e32 v22, 0x3fb8aa3b, v22
	v_mul_f32_e32 v23, 0x3fb8aa3b, v23
	v_exp_f32_e32 v20, v20
	v_exp_f32_e32 v21, v21
	v_exp_f32_e32 v22, v22
	v_exp_f32_e32 v23, v23
	v_cndmask_b32_e32 v20, 0, v20, vcc
	v_cndmask_b32_e64 v21, 0, v21, s[2:3]
	v_cndmask_b32_e64 v22, 0, v22, s[14:15]
	v_cndmask_b32_e64 v23, 0, v23, s[46:47]
	v_add_f32_e32 v3, v3, v20
	v_add_f32_e32 v3, v3, v21
	v_add_f32_e32 v3, v3, v22
	v_add_f32_e32 v3, v3, v23
	s_waitcnt lgkmcnt(10)
	v_cmp_lt_f32_e32 vcc, s75, v24
	v_cmp_lt_f32_e64 s[2:3], s75, v25
	v_cmp_lt_f32_e64 s[14:15], s75, v26
	v_cmp_lt_f32_e64 s[46:47], s75, v27
	v_sub_f32_e32 v24, v24, v2
	v_sub_f32_e32 v25, v25, v2
	v_sub_f32_e32 v26, v26, v2
	v_sub_f32_e32 v27, v27, v2
	v_mul_f32_e32 v24, 0x3fb8aa3b, v24
	v_mul_f32_e32 v25, 0x3fb8aa3b, v25
	v_mul_f32_e32 v26, 0x3fb8aa3b, v26
	v_mul_f32_e32 v27, 0x3fb8aa3b, v27
	v_exp_f32_e32 v24, v24
	v_exp_f32_e32 v25, v25
	v_exp_f32_e32 v26, v26
	v_exp_f32_e32 v27, v27
	v_cndmask_b32_e32 v24, 0, v24, vcc
	v_cndmask_b32_e64 v25, 0, v25, s[2:3]
	v_cndmask_b32_e64 v26, 0, v26, s[14:15]
	v_cndmask_b32_e64 v27, 0, v27, s[46:47]
	v_add_f32_e32 v3, v3, v24
	v_add_f32_e32 v3, v3, v25
	v_add_f32_e32 v3, v3, v26
	v_add_f32_e32 v3, v3, v27
	s_waitcnt lgkmcnt(8)
	v_cmp_lt_f32_e32 vcc, s75, v28
	v_cmp_lt_f32_e64 s[2:3], s75, v29
	v_cmp_lt_f32_e64 s[14:15], s75, v30
	v_cmp_lt_f32_e64 s[46:47], s75, v31
	v_sub_f32_e32 v28, v28, v2
	v_sub_f32_e32 v29, v29, v2
	v_sub_f32_e32 v30, v30, v2
	v_sub_f32_e32 v31, v31, v2
	v_mul_f32_e32 v28, 0x3fb8aa3b, v28
	v_mul_f32_e32 v29, 0x3fb8aa3b, v29
	v_mul_f32_e32 v30, 0x3fb8aa3b, v30
	v_mul_f32_e32 v31, 0x3fb8aa3b, v31
	v_exp_f32_e32 v28, v28
	v_exp_f32_e32 v29, v29
	v_exp_f32_e32 v30, v30
	v_exp_f32_e32 v31, v31
	v_cndmask_b32_e32 v28, 0, v28, vcc
	v_cndmask_b32_e64 v29, 0, v29, s[2:3]
	v_cndmask_b32_e64 v30, 0, v30, s[14:15]
	v_cndmask_b32_e64 v31, 0, v31, s[46:47]
	v_add_f32_e32 v3, v3, v28
	v_add_f32_e32 v3, v3, v29
	v_add_f32_e32 v3, v3, v30
	v_add_f32_e32 v3, v3, v31
	s_waitcnt lgkmcnt(6)
	v_cmp_lt_f32_e32 vcc, s75, v32
	v_cmp_lt_f32_e64 s[2:3], s75, v33
	v_cmp_lt_f32_e64 s[14:15], s75, v34
	v_cmp_lt_f32_e64 s[46:47], s75, v35
	v_sub_f32_e32 v32, v32, v2
	v_sub_f32_e32 v33, v33, v2
	v_sub_f32_e32 v34, v34, v2
	v_sub_f32_e32 v35, v35, v2
	v_mul_f32_e32 v32, 0x3fb8aa3b, v32
	v_mul_f32_e32 v33, 0x3fb8aa3b, v33
	v_mul_f32_e32 v34, 0x3fb8aa3b, v34
	v_mul_f32_e32 v35, 0x3fb8aa3b, v35
	v_exp_f32_e32 v32, v32
	v_exp_f32_e32 v33, v33
	v_exp_f32_e32 v34, v34
	v_exp_f32_e32 v35, v35
	v_cndmask_b32_e32 v32, 0, v32, vcc
	v_cndmask_b32_e64 v33, 0, v33, s[2:3]
	v_cndmask_b32_e64 v34, 0, v34, s[14:15]
	v_cndmask_b32_e64 v35, 0, v35, s[46:47]
	v_add_f32_e32 v3, v3, v32
	v_add_f32_e32 v3, v3, v33
	v_add_f32_e32 v3, v3, v34
	v_add_f32_e32 v3, v3, v35
	s_waitcnt lgkmcnt(4)
; __device__ __forceinline__ void dsa_item(const KP& p, int b, int tile, char* smem) {
;     ...
;     float sum = 0.f;
; #pragma unroll 4
;     for (int k = 0; k < 32; ++k) {
;       const int i = lane + 64 * k;
;       const float v = pbuf[i];
;       const float e = (v > -1e29f) ? __expf(v - mxh) : 0.f;
;       pbuf[i] = e;
;       sum += e;
;     }
;     sum += __shfl_xor(sum, 8);
;     sum += __shfl_xor(sum, 16);
;     sum += __shfl_xor(sum, 32);
;     const float inv = 1.f / sum;
;     __builtin_amdgcn_wave_barrier();
;     {
;       const int rs = lane >> 3, dc = lane & 7;
;       float acc[8][8];
; #pragma unroll
;       for (int h = 0; h < 8; ++h)
; #pragma unroll
;         for (int e = 0; e < 8; ++e) acc[h][e] = 0.f;
	v_cmp_lt_f32_e32 vcc, s75, v36
	v_cmp_lt_f32_e64 s[2:3], s75, v37
	v_cmp_lt_f32_e64 s[14:15], s75, v38
	v_cmp_lt_f32_e64 s[46:47], s75, v39
	v_sub_f32_e32 v36, v36, v2
	v_sub_f32_e32 v37, v37, v2
	v_sub_f32_e32 v38, v38, v2
	v_sub_f32_e32 v39, v39, v2
	v_mul_f32_e32 v36, 0x3fb8aa3b, v36
	v_mul_f32_e32 v37, 0x3fb8aa3b, v37
	v_mul_f32_e32 v38, 0x3fb8aa3b, v38
	v_mul_f32_e32 v39, 0x3fb8aa3b, v39
	v_exp_f32_e32 v36, v36
	v_exp_f32_e32 v37, v37
	v_exp_f32_e32 v38, v38
	v_exp_f32_e32 v39, v39
	v_cndmask_b32_e32 v36, 0, v36, vcc
	v_cndmask_b32_e64 v37, 0, v37, s[2:3]
	v_cndmask_b32_e64 v38, 0, v38, s[14:15]
	v_cndmask_b32_e64 v39, 0, v39, s[46:47]
	v_add_f32_e32 v3, v3, v36
	v_add_f32_e32 v3, v3, v37
	v_add_f32_e32 v3, v3, v38
	v_add_f32_e32 v3, v3, v39
	s_waitcnt lgkmcnt(2)
	v_cmp_lt_f32_e32 vcc, s75, v40
	v_cmp_lt_f32_e64 s[2:3], s75, v41
	v_cmp_lt_f32_e64 s[14:15], s75, v42
	v_cmp_lt_f32_e64 s[46:47], s75, v43
	v_sub_f32_e32 v40, v40, v2
	v_sub_f32_e32 v41, v41, v2
	v_sub_f32_e32 v42, v42, v2
	v_sub_f32_e32 v43, v43, v2
	v_mul_f32_e32 v40, 0x3fb8aa3b, v40
	v_mul_f32_e32 v41, 0x3fb8aa3b, v41
	v_mul_f32_e32 v42, 0x3fb8aa3b, v42
	v_mul_f32_e32 v43, 0x3fb8aa3b, v43
	v_exp_f32_e32 v40, v40
	v_exp_f32_e32 v41, v41
	v_exp_f32_e32 v42, v42
	v_exp_f32_e32 v43, v43
	v_cndmask_b32_e32 v40, 0, v40, vcc
	v_cndmask_b32_e64 v41, 0, v41, s[2:3]
	v_cndmask_b32_e64 v42, 0, v42, s[14:15]
	v_cndmask_b32_e64 v43, 0, v43, s[46:47]
	v_add_f32_e32 v3, v3, v40
	v_add_f32_e32 v3, v3, v41
	v_add_f32_e32 v3, v3, v42
	v_add_f32_e32 v3, v3, v43
	s_waitcnt lgkmcnt(0)
	v_cmp_lt_f32_e32 vcc, s75, v44
	v_cmp_lt_f32_e64 s[2:3], s75, v45
	v_cmp_lt_f32_e64 s[14:15], s75, v46
	v_cmp_lt_f32_e64 s[46:47], s75, v47
	v_sub_f32_e32 v44, v44, v2
	v_sub_f32_e32 v45, v45, v2
	v_sub_f32_e32 v46, v46, v2
	v_sub_f32_e32 v47, v47, v2
	v_mul_f32_e32 v44, 0x3fb8aa3b, v44
	v_mul_f32_e32 v45, 0x3fb8aa3b, v45
	v_mul_f32_e32 v46, 0x3fb8aa3b, v46
	v_mul_f32_e32 v47, 0x3fb8aa3b, v47
	v_exp_f32_e32 v44, v44
	v_exp_f32_e32 v45, v45
	v_exp_f32_e32 v46, v46
	v_exp_f32_e32 v47, v47
	v_cndmask_b32_e32 v44, 0, v44, vcc
	v_cndmask_b32_e64 v45, 0, v45, s[2:3]
	v_cndmask_b32_e64 v46, 0, v46, s[14:15]
	v_cndmask_b32_e64 v47, 0, v47, s[46:47]
	v_add_f32_e32 v3, v3, v44
	v_add_f32_e32 v3, v3, v45
	v_add_f32_e32 v3, v3, v46
	v_add_f32_e32 v3, v3, v47
	ds_write2st64_b32 v168, v16, v17 offset1:1
	ds_write2st64_b32 v168, v18, v19 offset0:2 offset1:3
	ds_write2st64_b32 v168, v20, v21 offset0:4 offset1:5
	ds_write2st64_b32 v168, v22, v23 offset0:6 offset1:7
	ds_write2st64_b32 v168, v24, v25 offset0:8 offset1:9
	ds_write2st64_b32 v168, v26, v27 offset0:10 offset1:11
	ds_write2st64_b32 v168, v28, v29 offset0:12 offset1:13
	ds_write2st64_b32 v168, v30, v31 offset0:14 offset1:15
	ds_write2st64_b32 v168, v32, v33 offset0:16 offset1:17
	ds_write2st64_b32 v168, v34, v35 offset0:18 offset1:19
	ds_write2st64_b32 v168, v36, v37 offset0:20 offset1:21
	ds_write2st64_b32 v168, v38, v39 offset0:22 offset1:23
	ds_write2st64_b32 v168, v40, v41 offset0:24 offset1:25
	ds_write2st64_b32 v168, v42, v43 offset0:26 offset1:27
	ds_write2st64_b32 v168, v44, v45 offset0:28 offset1:29
	ds_write2st64_b32 v168, v46, v47 offset0:30 offset1:31
	ds_bpermute_b32 v2, v164, v3
	v_mov_b32_e32 v98, 0
	s_mov_b32 s14, 0
	v_mov_b32_e32 v127, v170
	v_mov_b32_e32 v172, v169
	s_waitcnt lgkmcnt(0)
	v_add_f32_e32 v171, v3, v2
	ds_bpermute_b32 v173, v161, v171
	v_mov_b32_e32 v99, v98
	v_mov_b32_e32 v92, v98
	v_mov_b32_e32 v93, v98
	v_mov_b32_e32 v96, v98
	v_mov_b32_e32 v97, v98
	v_mov_b32_e32 v102, v98
	v_mov_b32_e32 v103, v98
	v_mov_b32_e32 v90, v98
	v_mov_b32_e32 v91, v98
	v_mov_b32_e32 v94, v98
	v_mov_b32_e32 v95, v98
	v_mov_b32_e32 v100, v98
	v_mov_b32_e32 v101, v98
	v_mov_b32_e32 v108, v98
	v_mov_b32_e32 v109, v98
	v_mov_b32_e32 v114, v98
	v_mov_b32_e32 v115, v98
	v_mov_b32_e32 v106, v98
	v_mov_b32_e32 v107, v98
	v_mov_b32_e32 v112, v98
	v_mov_b32_e32 v113, v98
	v_mov_b32_e32 v118, v98
	v_mov_b32_e32 v119, v98
	v_mov_b32_e32 v104, v98
	v_mov_b32_e32 v105, v98
	v_mov_b32_e32 v110, v98
	v_mov_b32_e32 v111, v98
	v_mov_b32_e32 v116, v98
	v_mov_b32_e32 v117, v98
	v_mov_b32_e32 v124, v98
	v_mov_b32_e32 v125, v98
	v_mov_b32_e32 v132, v98
	v_mov_b32_e32 v133, v98
	v_mov_b32_e32 v122, v98
	v_mov_b32_e32 v123, v98
	v_mov_b32_e32 v130, v98
	v_mov_b32_e32 v131, v98
	v_mov_b32_e32 v136, v98
	v_mov_b32_e32 v137, v98
	v_mov_b32_e32 v120, v98
	v_mov_b32_e32 v121, v98
	v_mov_b32_e32 v128, v98
	v_mov_b32_e32 v129, v98
	v_mov_b32_e32 v134, v98
	v_mov_b32_e32 v135, v98
	v_mov_b32_e32 v142, v98
	v_mov_b32_e32 v143, v98
	v_mov_b32_e32 v148, v98
	v_mov_b32_e32 v149, v98
	v_mov_b32_e32 v138, v98
	v_mov_b32_e32 v139, v98
	v_mov_b32_e32 v144, v98
	v_mov_b32_e32 v145, v98
	v_mov_b32_e32 v150, v98
	v_mov_b32_e32 v151, v98
	v_mov_b32_e32 v140, v98
	v_mov_b32_e32 v141, v98
	v_mov_b32_e32 v146, v98
	v_mov_b32_e32 v147, v98
	v_mov_b32_e32 v152, v98
	v_mov_b32_e32 v153, v98
	v_mov_b32_e32 v154, v98
	v_mov_b32_e32 v155, v98
	s_branch .LBB0_1513
